# MLA K-prep phase: all six loads of the next token issued at the top of the iteration into shadow registers (one round trip per token instead of three serial ones)
# baseline (speedup 1.0000x reference)
.LBB0_889:
	s_or_b64 exec, exec, s[4:5]
	v_mov_b32_e32 v6, v224
	s_mov_b64 s[4:5], s[0:1]
	s_waitcnt lgkmcnt(0)
	s_barrier
	s_load_dwordx2 s[8:9], s[4:5], 0xd8
	v_readfirstlane_b32 s3, v6
	s_mul_i32 s90, s55, 0x60
	s_ashr_i32 s3, s3, 6
	v_readlane_b32 s4, v255, 2
	s_add_i32 s6, s3, s4
	s_lshl_b64 s[4:5], s[90:91], 2
	s_waitcnt lgkmcnt(0)
	s_add_u32 s8, s8, s4
	v_and_b32_e32 v10, 15, v6
	s_addc_u32 s9, s9, s5
	v_lshlrev_b32_e32 v0, 4, v10
	v_lshlrev_b32_e32 v12, 2, v10
	global_load_dwordx4 v[0:3], v0, s[8:9]
	s_nop 0
	global_load_dword v4, v12, s[8:9] offset:256
	global_load_dword v5, v12, s[8:9] offset:320
	s_mov_b64 s[8:9], s[0:1]
	s_mov_b64 s[12:13], s[0:1]
	s_mov_b64 s[14:15], s[0:1]
	s_mov_b64 s[10:11], s[0:1]
	s_cmp_lt_i32 s6, 0x8000
	s_cbranch_scc0 .LBB0_892
	v_cvt_f32_ubyte0_e32 v7, v10
	v_mul_f32_e32 v8, 0xbf549a78, v7
	s_mov_b32 s3, 0xc2fc0000
	v_cmp_gt_f32_e32 vcc, s3, v8
	v_bfe_u32 v16, v6, 4, 2
	v_xor_b32_e32 v6, 1, v245
	v_cndmask_b32_e32 v9, 0, v232, vcc
	v_fmac_f32_e32 v9, 0xbf549a78, v7
	v_exp_f32_e32 v7, v9
	v_cndmask_b32_e32 v8, 0, v231, vcc
	s_load_dwordx2 s[14:15], s[14:15], 0xe8
	s_nop 0
	s_load_dwordx2 s[16:17], s[8:9], 0xe8
	s_nop 0
	s_load_dwordx2 s[12:13], s[12:13], 0xe8
	v_ldexp_f32 v17, v7, v8
	v_and_b32_e32 v7, 64, v245
	v_add_u32_e32 v7, 64, v7
	v_cmp_lt_i32_e32 vcc, v6, v7
	s_waitcnt lgkmcnt(0)
	s_add_u32 s8, s14, 0x18a00000
	s_addc_u32 s9, s15, 0
	v_cndmask_b32_e32 v6, v245, v6, vcc
	v_lshlrev_b32_e32 v18, 2, v6
	v_xor_b32_e32 v6, 2, v245
	v_cmp_lt_i32_e32 vcc, v6, v7
	s_ashr_i32 s7, s6, 31
	s_lshl_b64 s[14:15], s[6:7], 11
	v_cndmask_b32_e32 v6, v245, v6, vcc
	v_lshlrev_b32_e32 v19, 2, v6
	v_xor_b32_e32 v6, 4, v245
	v_cmp_lt_i32_e32 vcc, v6, v7
	s_load_dwordx2 s[10:11], s[10:11], 0x10
	s_add_u32 s14, s16, s14
	v_cndmask_b32_e32 v6, v245, v6, vcc
	v_lshlrev_b32_e32 v20, 2, v6
	v_xor_b32_e32 v6, 8, v245
	v_cmp_lt_i32_e32 vcc, v6, v7
	v_mov_b32_e32 v7, v113
	s_addc_u32 s15, s17, s15
	v_cndmask_b32_e32 v6, v245, v6, vcc
	v_lshlrev_b32_e32 v21, 2, v6
	v_lshlrev_b32_e32 v6, 1, v10
	v_lshl_add_u64 v[8:9], s[14:15], 0, v[6:7]
	s_mov_b64 s[14:15], 0x9200500
	v_lshl_add_u64 v[8:9], v[8:9], 0, s[14:15]
	s_lshl_b64 s[14:15], s[6:7], 2
	s_mul_hi_i32 s3, s6, 0x600
	s_mul_i32 s7, s6, 0x600
	v_lshlrev_b32_e32 v11, 7, v16
	v_lshlrev_b32_e32 v10, 3, v10
	v_or3_b32 v10, s7, v11, v10
	v_mov_b32_e32 v11, s3
	s_waitcnt lgkmcnt(0)
	s_add_u32 s10, s10, s14
	v_lshl_add_u64 v[10:11], s[12:13], 0, v[10:11]
	s_mov_b64 s[12:13], 0xd200200
	v_or_b32_e32 v22, 4, v16
	v_or_b32_e32 v23, 8, v16
	s_addc_u32 s11, s11, s15
	v_lshl_add_u64 v[10:11], v[10:11], 0, s[12:13]
	v_lshlrev_b32_e32 v112, 1, v12
	global_load_dwordx2 v[46:47], v[10:11], off offset:-512
	global_load_dwordx2 v[48:49], v[10:11], off
	global_load_dwordx2 v[50:51], v[10:11], off offset:512
	global_load_ushort v52, v[8:9], off
	global_load_ushort v53, v[8:9], off offset:32
	global_load_dword v54, v113, s[10:11]
	s_add_u32 s10, s10, s62
	s_addc_u32 s11, s11, s63
	v_lshl_add_u64 v[8:9], v[8:9], 0, s[50:51]
	v_lshl_add_u64 v[10:11], v[10:11], 0, s[96:97]
	s_waitcnt vmcnt(0)
.LBB0_891:
	v_mov_b32_e32 v14, v46
	v_mov_b32_e32 v15, v47
	v_mov_b32_e32 v55, v48
	v_mov_b32_e32 v56, v49
	v_mov_b32_e32 v57, v50
	v_mov_b32_e32 v58, v51
	v_mov_b32_e32 v32, v52
	v_mov_b32_e32 v33, v53
	v_mov_b32_e32 v28, v54
	s_add_i32 s7, s6, s28
	s_cmp_lt_i32 s7, 0x8000
	s_cbranch_scc0 .Lkprep_nopf
	global_load_dwordx2 v[46:47], v[10:11], off offset:-512
	global_load_dwordx2 v[48:49], v[10:11], off
	global_load_dwordx2 v[50:51], v[10:11], off offset:512
	global_load_ushort v52, v[8:9], off
	global_load_ushort v53, v[8:9], off offset:32
	global_load_dword v54, v113, s[10:11]
.Lkprep_nopf:
	s_ashr_i32 s12, s6, 14
	s_mul_i32 s12, s12, 12
	v_or_b32_e32 v24, s12, v16
	v_ashrrev_i32_e32 v25, 31, v24
	s_and_b32 s7, s6, 0x3fff
	v_lshlrev_b64 v[24:25], 14, v[24:25]
	v_mov_b64_e32 v[12:13], s[8:9]
	v_or_b32_e32 v24, s7, v24
	v_mad_u64_u32 v[26:27], s[14:15], v24, s94, v[12:13]
	v_mad_i32_i24 v27, v25, s94, v27
	v_lshl_add_u64 v[24:25], v[26:27], 0, v[112:113]
	v_lshl_add_u64 v[26:27], v[26:27], 0, v[6:7]
	s_add_i32 s6, s6, s28
	s_add_u32 s10, s10, s62
	s_addc_u32 s11, s11, s63
	v_lshl_add_u64 v[8:9], v[8:9], 0, s[50:51]
	s_cmpk_gt_i32 s6, 0x7fff
	v_and_b32_e32 v29, 0xffff0000, v15
	v_and_b32_e32 v31, 0xffff0000, v14
	v_lshlrev_b32_e32 v30, 16, v14
	v_cvt_f32_i32_e32 v38, v28
	v_lshlrev_b32_e32 v28, 16, v15
	v_lshlrev_b32_e32 v15, 16, v33
	v_lshlrev_b32_e32 v14, 16, v32
	v_mov_b32_e32 v36, v15
	v_mov_b32_e32 v37, v31
	v_pk_mul_f32 v[32:33], v[28:29], v[28:29]
	v_mov_b32_e32 v34, v14
	v_mov_b32_e32 v35, v30
	v_pk_mul_f32 v[36:37], v[36:37], v[36:37]
	v_add_f32_e32 v39, v32, v33
	v_pk_fma_f32 v[32:33], v[34:35], v[34:35], v[36:37]
	v_mul_f32_e32 v34, v17, v38
	v_add_f32_e32 v33, v33, v39
	v_add_f32_e32 v33, v32, v33
	ds_bpermute_b32 v38, v18, v33
	v_cvt_f64_f32_e32 v[34:35], v34
	v_mul_f64 v[36:37], v[34:35], s[48:49]
	v_rndne_f64_e32 v[36:37], v[36:37]
	v_fma_f64 v[34:35], v[34:35], s[48:49], -v[36:37]
	v_cvt_f32_f64_e32 v35, v[34:35]
	s_waitcnt lgkmcnt(0)
	v_add_f32_e32 v33, v33, v38
	v_sin_f32_e32 v34, v35
	v_cos_f32_e32 v36, v35
	ds_bpermute_b32 v35, v19, v33
	s_waitcnt lgkmcnt(0)
	v_add_f32_e32 v33, v33, v35
	ds_bpermute_b32 v35, v20, v33
	s_waitcnt lgkmcnt(0)
	v_add_f32_e32 v33, v33, v35
	ds_bpermute_b32 v35, v21, v33
	s_waitcnt lgkmcnt(0)
	v_add_f32_e32 v33, v33, v35
	v_fmamk_f32 v33, v33, 0x3c2aaaab, v229
	v_mul_f32_e32 v35, 0x4b800000, v33
	v_cmp_gt_f32_e32 vcc, s65, v33
	s_nop 1
	v_cndmask_b32_e32 v33, v33, v35, vcc
	v_rsq_f32_e32 v33, v33
	s_nop 0
	v_mul_f32_e32 v35, 0x45800000, v33
	v_cndmask_b32_e32 v38, v33, v35, vcc
	v_pk_mul_f32 v[30:31], v[38:39], v[30:31] op_sel_hi:[0,1]
	v_pk_mul_f32 v[28:29], v[38:39], v[28:29] op_sel_hi:[0,1]
	v_pk_mul_f32 v[38:39], v[38:39], v[14:15] op_sel_hi:[0,1]
	v_pk_mul_f32 v[30:31], v[0:1], v[30:31]
	v_pk_mul_f32 v[28:29], v[2:3], v[28:29]
	v_pk_mul_f32 v[38:39], v[4:5], v[38:39]
	v_cvt_pk_bf16_f32 v30, v30, v31
	v_cvt_pk_bf16_f32 v31, v28, v29
	v_pk_mul_f32 v[28:29], v[34:35], v[38:39] op_sel_hi:[0,1]
	global_store_dwordx2 v[24:25], v[30:31], off
	v_pk_fma_f32 v[24:25], v[36:37], v[38:39], v[28:29] op_sel:[0,0,1] op_sel_hi:[1,1,0] neg_lo:[0,0,1] neg_hi:[0,0,1]
	v_pk_fma_f32 v[28:29], v[36:37], v[38:39], v[28:29] op_sel:[0,0,1] op_sel_hi:[0,1,0]
	v_cvt_pk_bf16_f32 v24, v24, v29
	global_store_short v[26:27], v24, off offset:128
	global_store_short_d16_hi v[26:27], v24, off offset:160
	v_mov_b32_e32 v24, v55
	v_mov_b32_e32 v25, v56
	v_add_u32_e32 v26, s12, v22
	v_ashrrev_i32_e32 v27, 31, v26
	v_lshlrev_b64 v[26:27], 14, v[26:27]
	v_or_b32_e32 v26, s7, v26
	v_mad_u64_u32 v[28:29], s[14:15], v26, s94, v[12:13]
	v_mad_i32_i24 v29, v27, s94, v29
	v_lshl_add_u64 v[26:27], v[28:29], 0, v[112:113]
	v_lshl_add_u64 v[28:29], v[28:29], 0, v[6:7]
	v_and_b32_e32 v31, 0xffff0000, v25
	v_and_b32_e32 v39, 0xffff0000, v24
	v_lshlrev_b32_e32 v30, 16, v25
	v_lshlrev_b32_e32 v38, 16, v24
	v_mov_b32_e32 v40, v39
	v_mov_b32_e32 v41, v31
	v_mov_b32_e32 v24, v38
	v_mov_b32_e32 v25, v30
	v_pk_mul_f32 v[40:41], v[40:41], v[40:41]
	s_nop 0
	v_pk_fma_f32 v[24:25], v[24:25], v[24:25], v[40:41]
	s_nop 0
	v_add_f32_e32 v24, v24, v25
	v_add_f32_e32 v24, v32, v24
	ds_bpermute_b32 v25, v18, v24
	s_waitcnt lgkmcnt(0)
	v_add_f32_e32 v24, v24, v25
	ds_bpermute_b32 v25, v19, v24
	s_waitcnt lgkmcnt(0)
	v_add_f32_e32 v24, v24, v25
	ds_bpermute_b32 v25, v20, v24
	s_waitcnt lgkmcnt(0)
	v_add_f32_e32 v24, v24, v25
	ds_bpermute_b32 v25, v21, v24
	s_waitcnt lgkmcnt(0)
	v_add_f32_e32 v24, v24, v25
	v_fmamk_f32 v24, v24, 0x3c2aaaab, v229
	v_mul_f32_e32 v25, 0x4b800000, v24
	v_cmp_gt_f32_e32 vcc, s65, v24
	s_nop 1
	v_cndmask_b32_e32 v24, v24, v25, vcc
	v_rsq_f32_e32 v24, v24
	s_nop 0
	v_mul_f32_e32 v25, 0x45800000, v24
	v_cndmask_b32_e32 v24, v24, v25, vcc
	v_pk_mul_f32 v[38:39], v[24:25], v[38:39] op_sel_hi:[0,1]
	v_pk_mul_f32 v[30:31], v[24:25], v[30:31] op_sel_hi:[0,1]
	v_pk_mul_f32 v[24:25], v[24:25], v[14:15] op_sel_hi:[0,1]
	v_pk_mul_f32 v[38:39], v[0:1], v[38:39]
	v_pk_mul_f32 v[30:31], v[2:3], v[30:31]
	v_pk_mul_f32 v[24:25], v[4:5], v[24:25]
	v_cvt_pk_bf16_f32 v38, v38, v39
	v_cvt_pk_bf16_f32 v39, v30, v31
	v_pk_mul_f32 v[30:31], v[34:35], v[24:25] op_sel_hi:[0,1]
	global_store_dwordx2 v[26:27], v[38:39], off
	v_pk_fma_f32 v[26:27], v[36:37], v[24:25], v[30:31] op_sel:[0,0,1] op_sel_hi:[1,1,0] neg_lo:[0,0,1] neg_hi:[0,0,1]
	v_pk_fma_f32 v[24:25], v[36:37], v[24:25], v[30:31] op_sel:[0,0,1] op_sel_hi:[0,1,0]
	v_cvt_pk_bf16_f32 v24, v26, v25
	global_store_short v[28:29], v24, off offset:128
	global_store_short_d16_hi v[28:29], v24, off offset:160
	v_mov_b32_e32 v24, v57
	v_mov_b32_e32 v25, v58
	v_add_u32_e32 v26, s12, v23
	v_ashrrev_i32_e32 v27, 31, v26
	v_lshlrev_b64 v[26:27], 14, v[26:27]
	v_or_b32_e32 v26, s7, v26
	v_mad_u64_u32 v[12:13], s[12:13], v26, s94, v[12:13]
	v_mad_i32_i24 v13, v27, s94, v13
	v_lshl_add_u64 v[26:27], v[12:13], 0, v[112:113]
	v_lshl_add_u64 v[12:13], v[12:13], 0, v[6:7]
	v_lshl_add_u64 v[10:11], v[10:11], 0, s[96:97]
	v_and_b32_e32 v29, 0xffff0000, v25
	v_and_b32_e32 v31, 0xffff0000, v24
	v_lshlrev_b32_e32 v28, 16, v25
	v_lshlrev_b32_e32 v30, 16, v24
	v_mov_b32_e32 v38, v31
	v_mov_b32_e32 v39, v29
	v_mov_b32_e32 v24, v30
	v_mov_b32_e32 v25, v28
	v_pk_mul_f32 v[38:39], v[38:39], v[38:39]
	s_nop 0
	v_pk_fma_f32 v[24:25], v[24:25], v[24:25], v[38:39]
	s_nop 0
	v_add_f32_e32 v24, v24, v25
	v_add_f32_e32 v24, v32, v24
	ds_bpermute_b32 v25, v18, v24
	s_waitcnt lgkmcnt(0)
	v_add_f32_e32 v24, v24, v25
	ds_bpermute_b32 v25, v19, v24
	s_waitcnt lgkmcnt(0)
	v_add_f32_e32 v24, v24, v25
	ds_bpermute_b32 v25, v20, v24
	s_waitcnt lgkmcnt(0)
	v_add_f32_e32 v24, v24, v25
	ds_bpermute_b32 v25, v21, v24
	s_waitcnt lgkmcnt(0)
	v_add_f32_e32 v24, v24, v25
	v_fmamk_f32 v24, v24, 0x3c2aaaab, v229
	v_mul_f32_e32 v25, 0x4b800000, v24
	v_cmp_gt_f32_e32 vcc, s65, v24
	s_nop 1
	v_cndmask_b32_e32 v24, v24, v25, vcc
	v_rsq_f32_e32 v24, v24
	s_nop 0
	v_mul_f32_e32 v25, 0x45800000, v24
	v_cndmask_b32_e32 v24, v24, v25, vcc
	v_pk_mul_f32 v[30:31], v[24:25], v[30:31] op_sel_hi:[0,1]
	v_pk_mul_f32 v[28:29], v[24:25], v[28:29] op_sel_hi:[0,1]
	v_pk_mul_f32 v[14:15], v[24:25], v[14:15] op_sel_hi:[0,1]
	v_pk_mul_f32 v[24:25], v[0:1], v[30:31]
	v_pk_mul_f32 v[28:29], v[2:3], v[28:29]
	v_pk_mul_f32 v[14:15], v[4:5], v[14:15]
	v_cvt_pk_bf16_f32 v24, v24, v25
	v_cvt_pk_bf16_f32 v25, v28, v29
	v_pk_mul_f32 v[28:29], v[34:35], v[14:15] op_sel_hi:[0,1]
	global_store_dwordx2 v[26:27], v[24:25], off
	v_pk_fma_f32 v[24:25], v[36:37], v[14:15], v[28:29] op_sel:[0,0,1] op_sel_hi:[1,1,0] neg_lo:[0,0,1] neg_hi:[0,0,1]
	v_pk_fma_f32 v[14:15], v[36:37], v[14:15], v[28:29] op_sel:[0,0,1] op_sel_hi:[0,1,0]
	v_cvt_pk_bf16_f32 v14, v24, v15
	global_store_short v[12:13], v14, off offset:128
	global_store_short_d16_hi v[12:13], v14, off offset:160
	s_waitcnt vmcnt(9)
	s_cbranch_scc0 .LBB0_891
